# P11 epilogue: per-row sum-of-squares loads issued in the last K iteration instead of after the loop
# speedup vs baseline: 1.0053x; 1.0053x over previous
.LBB0_2109:
	ds_read_b128 v[146:149], v157
	ds_read_b128 v[168:171], v157 offset:1024
	ds_read_b128 v[172:175], v157 offset:2048
	ds_read_b128 v[176:179], v157 offset:3072
	ds_read_b128 v[184:187], v159
	ds_read_b128 v[188:191], v159 offset:1024
	ds_read_b128 v[192:195], v159 offset:2048
	ds_read_b128 v[196:199], v159 offset:3072
	s_add_u32 s6, s4, 0xfffc0080
	s_addc_u32 s7, s5, -1
	s_cmp_eq_u32 s63, 12
	s_cselect_b32 s37, s29, s7
	s_cselect_b32 s36, s59, s6
	s_cselect_b32 s7, s27, s62
	s_cselect_b32 s6, s60, s61
	v_lshl_add_u64 v[152:153], s[4:5], 0, v[138:139]
	s_add_i32 m0, s44, 0xc000
	ds_read_b128 v[200:203], v163
	ds_read_b128 v[204:207], v163 offset:1024
	ds_read_b128 v[208:211], v163 offset:2048
	ds_read_b128 v[212:215], v163 offset:3072
	ds_read_b128 v[216:219], v163 offset:4096
	ds_read_b128 v[220:223], v163 offset:5120
	ds_read_b128 v[224:227], v163 offset:6144
	ds_read_b128 v[228:231], v163 offset:7168
	global_load_lds_dwordx4 v[152:153], off
	v_lshl_add_u64 v[152:153], s[4:5], 0, v[140:141]
	s_add_i32 m0, s44, 0xe000
	s_nop 0
	global_load_lds_dwordx4 v[152:153], off
	s_waitcnt vmcnt(8)
	s_waitcnt lgkmcnt(0)
	s_barrier
	s_setprio 1
	s_waitcnt lgkmcnt(0)
	v_mfma_f32_16x16x32_bf16 v[124:127], v[146:149], v[200:203], v[124:127]
	v_mfma_f32_16x16x32_bf16 v[120:123], v[172:175], v[200:203], v[120:123]
	v_mfma_f32_16x16x32_bf16 v[108:111], v[146:149], v[208:211], v[108:111]
	v_mfma_f32_16x16x32_bf16 v[104:107], v[172:175], v[208:211], v[104:107]
	v_mfma_f32_16x16x32_bf16 v[92:95], v[146:149], v[216:219], v[92:95]
	v_mfma_f32_16x16x32_bf16 v[88:91], v[172:175], v[216:219], v[88:91]
	v_mfma_f32_16x16x32_bf16 v[76:79], v[146:149], v[224:227], v[76:79]
	v_mfma_f32_16x16x32_bf16 v[72:75], v[172:175], v[224:227], v[72:75]
	v_mfma_f32_16x16x32_bf16 v[124:127], v[168:171], v[204:207], v[124:127]
	v_mfma_f32_16x16x32_bf16 v[120:123], v[176:179], v[204:207], v[120:123]
	v_mfma_f32_16x16x32_bf16 v[108:111], v[168:171], v[212:215], v[108:111]
	v_mfma_f32_16x16x32_bf16 v[104:107], v[176:179], v[212:215], v[104:107]
	v_mfma_f32_16x16x32_bf16 v[92:95], v[168:171], v[220:223], v[92:95]
	v_mfma_f32_16x16x32_bf16 v[88:91], v[176:179], v[220:223], v[88:91]
	v_mfma_f32_16x16x32_bf16 v[76:79], v[168:171], v[228:231], v[76:79]
	v_mfma_f32_16x16x32_bf16 v[72:75], v[176:179], v[228:231], v[72:75]
	s_setprio 0
	s_setprio 1
	v_mfma_f32_16x16x32_bf16 v[116:119], v[184:187], v[200:203], v[116:119]
	v_mfma_f32_16x16x32_bf16 v[112:115], v[192:195], v[200:203], v[112:115]
	v_mfma_f32_16x16x32_bf16 v[100:103], v[184:187], v[208:211], v[100:103]
	v_mfma_f32_16x16x32_bf16 v[96:99], v[192:195], v[208:211], v[96:99]
	v_mfma_f32_16x16x32_bf16 v[84:87], v[184:187], v[216:219], v[84:87]
	v_mfma_f32_16x16x32_bf16 v[80:83], v[192:195], v[216:219], v[80:83]
	v_mfma_f32_16x16x32_bf16 v[68:71], v[184:187], v[224:227], v[68:71]
	v_mfma_f32_16x16x32_bf16 v[64:67], v[192:195], v[224:227], v[64:67]
	v_mfma_f32_16x16x32_bf16 v[116:119], v[188:191], v[204:207], v[116:119]
	v_mfma_f32_16x16x32_bf16 v[112:115], v[196:199], v[204:207], v[112:115]
	v_mfma_f32_16x16x32_bf16 v[100:103], v[188:191], v[212:215], v[100:103]
	v_mfma_f32_16x16x32_bf16 v[96:99], v[196:199], v[212:215], v[96:99]
	v_mfma_f32_16x16x32_bf16 v[84:87], v[188:191], v[220:223], v[84:87]
	v_mfma_f32_16x16x32_bf16 v[80:83], v[196:199], v[220:223], v[80:83]
	v_mfma_f32_16x16x32_bf16 v[68:71], v[188:191], v[228:231], v[68:71]
	v_mfma_f32_16x16x32_bf16 v[64:67], v[196:199], v[228:231], v[64:67]
	s_setprio 0
	s_barrier
	s_add_i32 s64, s52, s41
	v_lshl_add_u64 v[152:153], s[6:7], 0, v[132:133]
	s_mov_b32 m0, s64
	ds_read_b128 v[200:203], v163 offset:16384
	ds_read_b128 v[204:207], v163 offset:17408
	ds_read_b128 v[208:211], v163 offset:18432
	ds_read_b128 v[212:215], v163 offset:19456
	ds_read_b128 v[216:219], v163 offset:20480
	ds_read_b128 v[220:223], v163 offset:21504
	ds_read_b128 v[224:227], v163 offset:22528
	ds_read_b128 v[228:231], v163 offset:23552
	global_load_lds_dwordx4 v[152:153], off
	s_add_i32 m0, s64, 0x2000
	s_add_u32 s64, s6, 0x40000
	v_lshl_add_u64 v[160:161], s[6:7], 0, v[128:129]
	s_addc_u32 s65, s7, 0
	s_add_i32 s66, s53, s41
	global_load_lds_dwordx4 v[160:161], off
	v_lshl_add_u64 v[180:181], s[64:65], 0, v[132:133]
	s_mov_b32 m0, s66
	v_lshl_add_u64 v[232:233], s[36:37], 0, v[130:131]
	global_load_lds_dwordx4 v[180:181], off
	v_lshl_add_u64 v[180:181], s[64:65], 0, v[128:129]
	s_add_i32 m0, s66, 0x2000
	s_nop 0
	global_load_lds_dwordx4 v[180:181], off
	v_lshl_add_u64 v[180:181], s[36:37], 0, v[134:135]
	s_mov_b32 m0, s44
	s_nop 0
	global_load_lds_dwordx4 v[180:181], off
	s_mov_b32 m0, s45
	s_nop 0
	global_load_lds_dwordx4 v[232:233], off
	s_waitcnt vmcnt(8)
	s_waitcnt lgkmcnt(0)
	s_barrier
	s_setprio 1
	s_waitcnt lgkmcnt(0)
	v_mfma_f32_16x16x32_bf16 v[60:63], v[146:149], v[200:203], v[60:63]
	v_mfma_f32_16x16x32_bf16 v[56:59], v[172:175], v[200:203], v[56:59]
	v_mfma_f32_16x16x32_bf16 v[44:47], v[146:149], v[208:211], v[44:47]
	v_mfma_f32_16x16x32_bf16 v[40:43], v[172:175], v[208:211], v[40:43]
	v_mfma_f32_16x16x32_bf16 v[28:31], v[146:149], v[216:219], v[28:31]
	v_mfma_f32_16x16x32_bf16 v[24:27], v[172:175], v[216:219], v[24:27]
	v_mfma_f32_16x16x32_bf16 v[12:15], v[146:149], v[224:227], v[12:15]
	v_mfma_f32_16x16x32_bf16 v[8:11], v[172:175], v[224:227], v[8:11]
	v_mfma_f32_16x16x32_bf16 v[60:63], v[168:171], v[204:207], v[60:63]
	v_mfma_f32_16x16x32_bf16 v[56:59], v[176:179], v[204:207], v[56:59]
	v_mfma_f32_16x16x32_bf16 v[44:47], v[168:171], v[212:215], v[44:47]
	v_mfma_f32_16x16x32_bf16 v[40:43], v[176:179], v[212:215], v[40:43]
	v_mfma_f32_16x16x32_bf16 v[28:31], v[168:171], v[220:223], v[28:31]
	v_mfma_f32_16x16x32_bf16 v[24:27], v[176:179], v[220:223], v[24:27]
	v_mfma_f32_16x16x32_bf16 v[12:15], v[168:171], v[228:231], v[12:15]
	v_mfma_f32_16x16x32_bf16 v[8:11], v[176:179], v[228:231], v[8:11]
	s_setprio 0
	s_setprio 1
	v_mfma_f32_16x16x32_bf16 v[52:55], v[184:187], v[200:203], v[52:55]
	v_mfma_f32_16x16x32_bf16 v[48:51], v[192:195], v[200:203], v[48:51]
	v_mfma_f32_16x16x32_bf16 v[36:39], v[184:187], v[208:211], v[36:39]
	v_mfma_f32_16x16x32_bf16 v[32:35], v[192:195], v[208:211], v[32:35]
	v_mfma_f32_16x16x32_bf16 v[20:23], v[184:187], v[216:219], v[20:23]
	v_mfma_f32_16x16x32_bf16 v[16:19], v[192:195], v[216:219], v[16:19]
	v_mfma_f32_16x16x32_bf16 v[4:7], v[184:187], v[224:227], v[4:7]
	v_mfma_f32_16x16x32_bf16 v[0:3], v[192:195], v[224:227], v[0:3]
	v_mfma_f32_16x16x32_bf16 v[52:55], v[188:191], v[204:207], v[52:55]
	v_mfma_f32_16x16x32_bf16 v[48:51], v[196:199], v[204:207], v[48:51]
	v_mfma_f32_16x16x32_bf16 v[36:39], v[188:191], v[212:215], v[36:39]
	v_mfma_f32_16x16x32_bf16 v[32:35], v[196:199], v[212:215], v[32:35]
	v_mfma_f32_16x16x32_bf16 v[20:23], v[188:191], v[220:223], v[20:23]
	v_mfma_f32_16x16x32_bf16 v[16:19], v[196:199], v[220:223], v[16:19]
	v_mfma_f32_16x16x32_bf16 v[4:7], v[188:191], v[228:231], v[4:7]
	v_mfma_f32_16x16x32_bf16 v[0:3], v[196:199], v[228:231], v[0:3]
	s_setprio 0
	s_barrier
	s_add_i32 s64, 0, 0x18000
	v_add_u32_e32 v150, s64, v155
	s_add_i32 s65, 0, 0x1c000
	ds_read_b128 v[146:149], v150
	ds_read_b128 v[168:171], v150 offset:1024
	ds_read_b128 v[172:175], v150 offset:2048
	ds_read_b128 v[176:179], v150 offset:3072
	v_add_u32_e32 v150, s65, v155
	ds_read_b128 v[184:187], v150
	ds_read_b128 v[188:191], v150 offset:1024
	ds_read_b128 v[192:195], v150 offset:2048
	ds_read_b128 v[196:199], v150 offset:3072
	s_add_u32 s36, s36, 0x40000
	s_addc_u32 s37, s37, 0
	s_mov_b32 m0, s46
	v_lshl_add_u64 v[234:235], s[36:37], 0, v[134:135]
	ds_read_b128 v[200:203], v163 offset:32768
	ds_read_b128 v[204:207], v163 offset:33792
	ds_read_b128 v[208:211], v163 offset:34816
	ds_read_b128 v[212:215], v163 offset:35840
	ds_read_b128 v[216:219], v163 offset:36864
	ds_read_b128 v[220:223], v163 offset:37888
	ds_read_b128 v[224:227], v163 offset:38912
	ds_read_b128 v[228:231], v163 offset:39936
	global_load_lds_dwordx4 v[234:235], off
	v_lshl_add_u64 v[234:235], s[36:37], 0, v[130:131]
	s_mov_b32 m0, s47
	s_nop 0
	global_load_lds_dwordx4 v[234:235], off
	s_waitcnt vmcnt(8)
	s_waitcnt lgkmcnt(0)
	s_barrier
	s_setprio 1
	s_waitcnt lgkmcnt(0)
	v_mfma_f32_16x16x32_bf16 v[124:127], v[146:149], v[200:203], v[124:127]
	v_mfma_f32_16x16x32_bf16 v[120:123], v[172:175], v[200:203], v[120:123]
	v_mfma_f32_16x16x32_bf16 v[108:111], v[146:149], v[208:211], v[108:111]
	v_mfma_f32_16x16x32_bf16 v[104:107], v[172:175], v[208:211], v[104:107]
	v_mfma_f32_16x16x32_bf16 v[92:95], v[146:149], v[216:219], v[92:95]
	v_mfma_f32_16x16x32_bf16 v[88:91], v[172:175], v[216:219], v[88:91]
	v_mfma_f32_16x16x32_bf16 v[76:79], v[146:149], v[224:227], v[76:79]
	v_mfma_f32_16x16x32_bf16 v[72:75], v[172:175], v[224:227], v[72:75]
	v_mfma_f32_16x16x32_bf16 v[124:127], v[168:171], v[204:207], v[124:127]
	v_mfma_f32_16x16x32_bf16 v[120:123], v[176:179], v[204:207], v[120:123]
	v_mfma_f32_16x16x32_bf16 v[108:111], v[168:171], v[212:215], v[108:111]
	v_mfma_f32_16x16x32_bf16 v[104:107], v[176:179], v[212:215], v[104:107]
	v_mfma_f32_16x16x32_bf16 v[92:95], v[168:171], v[220:223], v[92:95]
	v_mfma_f32_16x16x32_bf16 v[88:91], v[176:179], v[220:223], v[88:91]
	v_mfma_f32_16x16x32_bf16 v[76:79], v[168:171], v[228:231], v[76:79]
	v_mfma_f32_16x16x32_bf16 v[72:75], v[176:179], v[228:231], v[72:75]
	s_setprio 0
	s_setprio 1
	v_mfma_f32_16x16x32_bf16 v[116:119], v[184:187], v[200:203], v[116:119]
	v_mfma_f32_16x16x32_bf16 v[112:115], v[192:195], v[200:203], v[112:115]
	v_mfma_f32_16x16x32_bf16 v[100:103], v[184:187], v[208:211], v[100:103]
	v_mfma_f32_16x16x32_bf16 v[96:99], v[192:195], v[208:211], v[96:99]
	v_mfma_f32_16x16x32_bf16 v[84:87], v[184:187], v[216:219], v[84:87]
	v_mfma_f32_16x16x32_bf16 v[80:83], v[192:195], v[216:219], v[80:83]
	v_mfma_f32_16x16x32_bf16 v[68:71], v[184:187], v[224:227], v[68:71]
	v_mfma_f32_16x16x32_bf16 v[64:67], v[192:195], v[224:227], v[64:67]
	v_mfma_f32_16x16x32_bf16 v[116:119], v[188:191], v[204:207], v[116:119]
	v_mfma_f32_16x16x32_bf16 v[112:115], v[196:199], v[204:207], v[112:115]
	v_mfma_f32_16x16x32_bf16 v[100:103], v[188:191], v[212:215], v[100:103]
	v_mfma_f32_16x16x32_bf16 v[96:99], v[196:199], v[212:215], v[96:99]
	v_mfma_f32_16x16x32_bf16 v[84:87], v[188:191], v[220:223], v[84:87]
	v_mfma_f32_16x16x32_bf16 v[80:83], v[196:199], v[220:223], v[80:83]
	v_mfma_f32_16x16x32_bf16 v[68:71], v[188:191], v[228:231], v[68:71]
	v_mfma_f32_16x16x32_bf16 v[64:67], v[196:199], v[228:231], v[64:67]
	s_setprio 0
	s_barrier
	s_add_i32 s36, s64, s41
	v_lshl_add_u64 v[152:153], v[152:153], 0, s[14:15]
	s_mov_b32 m0, s36
	ds_read_b128 v[200:203], v163 offset:49152
	ds_read_b128 v[204:207], v163 offset:50176
	ds_read_b128 v[208:211], v163 offset:51200
	ds_read_b128 v[212:215], v163 offset:52224
	ds_read_b128 v[216:219], v163 offset:53248
	ds_read_b128 v[220:223], v163 offset:54272
	ds_read_b128 v[224:227], v163 offset:55296
	ds_read_b128 v[228:231], v163 offset:56320
	global_load_lds_dwordx4 v[152:153], off
	s_add_i32 m0, s36, 0x2000
	s_add_u32 s6, s6, 0x40080
	v_lshl_add_u64 v[152:153], v[160:161], 0, s[14:15]
	s_addc_u32 s7, s7, 0
	s_add_i32 s36, s65, s41
	global_load_lds_dwordx4 v[152:153], off
	v_lshl_add_u64 v[152:153], s[6:7], 0, v[132:133]
	s_mov_b32 m0, s36
	s_nop 0
	global_load_lds_dwordx4 v[152:153], off
	v_lshl_add_u64 v[152:153], s[6:7], 0, v[128:129]
	s_add_i32 m0, s36, 0x2000
	s_nop 0
	global_load_lds_dwordx4 v[152:153], off
	v_lshl_add_u64 v[152:153], v[180:181], 0, s[14:15]
	s_mov_b32 m0, s49
	s_nop 0
	global_load_lds_dwordx4 v[152:153], off
	v_lshl_add_u64 v[152:153], v[232:233], 0, s[14:15]
	s_mov_b32 m0, s50
	s_nop 0
	global_load_lds_dwordx4 v[152:153], off
	s_waitcnt vmcnt(8)
	s_cmp_eq_u32 s63, 12
	s_cbranch_scc0 .Lp11_nopf
	v_lshl_add_u32 v254, s2, 8, v151
	v_ashrrev_i32_e32 v255, 31, v254
	v_lshl_add_u64 v[254:255], v[254:255], 2, s[12:13]
	global_load_dword v245, v[254:255], off
	global_load_dword v246, v[254:255], off offset:64
	global_load_dword v247, v[254:255], off offset:128
	global_load_dword v248, v[254:255], off offset:192
	global_load_dword v249, v[254:255], off offset:512
	global_load_dword v250, v[254:255], off offset:576
	global_load_dword v251, v[254:255], off offset:640
	global_load_dword v252, v[254:255], off offset:704
.Lp11_nopf:
	s_waitcnt lgkmcnt(0)
	s_barrier
	s_setprio 1
	s_waitcnt lgkmcnt(0)
	v_mfma_f32_16x16x32_bf16 v[60:63], v[146:149], v[200:203], v[60:63]
	v_mfma_f32_16x16x32_bf16 v[56:59], v[172:175], v[200:203], v[56:59]
	v_mfma_f32_16x16x32_bf16 v[44:47], v[146:149], v[208:211], v[44:47]
	v_mfma_f32_16x16x32_bf16 v[40:43], v[172:175], v[208:211], v[40:43]
	v_mfma_f32_16x16x32_bf16 v[28:31], v[146:149], v[216:219], v[28:31]
	v_mfma_f32_16x16x32_bf16 v[24:27], v[172:175], v[216:219], v[24:27]
	v_mfma_f32_16x16x32_bf16 v[12:15], v[146:149], v[224:227], v[12:15]
	v_mfma_f32_16x16x32_bf16 v[8:11], v[172:175], v[224:227], v[8:11]
	v_mfma_f32_16x16x32_bf16 v[60:63], v[168:171], v[204:207], v[60:63]
	v_mfma_f32_16x16x32_bf16 v[56:59], v[176:179], v[204:207], v[56:59]
	v_mfma_f32_16x16x32_bf16 v[44:47], v[168:171], v[212:215], v[44:47]
	v_mfma_f32_16x16x32_bf16 v[40:43], v[176:179], v[212:215], v[40:43]
	v_mfma_f32_16x16x32_bf16 v[28:31], v[168:171], v[220:223], v[28:31]
	v_mfma_f32_16x16x32_bf16 v[24:27], v[176:179], v[220:223], v[24:27]
	v_mfma_f32_16x16x32_bf16 v[12:15], v[168:171], v[228:231], v[12:15]
	v_mfma_f32_16x16x32_bf16 v[8:11], v[176:179], v[228:231], v[8:11]
	s_setprio 0
	s_setprio 1
	v_mfma_f32_16x16x32_bf16 v[52:55], v[184:187], v[200:203], v[52:55]
	v_mfma_f32_16x16x32_bf16 v[48:51], v[192:195], v[200:203], v[48:51]
	v_mfma_f32_16x16x32_bf16 v[36:39], v[184:187], v[208:211], v[36:39]
	v_mfma_f32_16x16x32_bf16 v[32:35], v[192:195], v[208:211], v[32:35]
	v_mfma_f32_16x16x32_bf16 v[20:23], v[184:187], v[216:219], v[20:23]
	v_mfma_f32_16x16x32_bf16 v[16:19], v[192:195], v[216:219], v[16:19]
	v_mfma_f32_16x16x32_bf16 v[4:7], v[184:187], v[224:227], v[4:7]
	v_mfma_f32_16x16x32_bf16 v[0:3], v[192:195], v[224:227], v[0:3]
	v_mfma_f32_16x16x32_bf16 v[52:55], v[188:191], v[204:207], v[52:55]
	v_mfma_f32_16x16x32_bf16 v[48:51], v[196:199], v[204:207], v[48:51]
	v_mfma_f32_16x16x32_bf16 v[36:39], v[188:191], v[212:215], v[36:39]
	v_mfma_f32_16x16x32_bf16 v[32:35], v[196:199], v[212:215], v[32:35]
	v_mfma_f32_16x16x32_bf16 v[20:23], v[188:191], v[220:223], v[20:23]
	v_mfma_f32_16x16x32_bf16 v[16:19], v[196:199], v[220:223], v[16:19]
	v_mfma_f32_16x16x32_bf16 v[4:7], v[188:191], v[228:231], v[4:7]
	v_mfma_f32_16x16x32_bf16 v[0:3], v[196:199], v[228:231], v[0:3]
	s_setprio 0
	s_barrier
	s_add_i32 s63, s63, 2
	s_add_u32 s4, s4, 0x100
	s_addc_u32 s5, s5, 0
	s_add_u32 s61, s61, 0x100
	s_addc_u32 s62, s62, 0
	s_cmp_gt_u32 s63, 13
	s_cbranch_scc0 .LBB0_2109
	s_and_b64 vcc, exec, s[16:17]
	s_cbranch_vccz .LBB0_2112
	s_barrier
.LBB0_2112:
	v_lshl_add_u32 v160, s2, 8, v151
	v_ashrrev_i32_e32 v161, 31, v160
	v_lshl_add_u64 v[168:169], v[160:161], 2, s[12:13]
	s_nop 0
	v_or_b32_e32 v152, 16, v160
	v_ashrrev_i32_e32 v153, 31, v152
	v_or_b32_e32 v148, 32, v160
	v_or_b32_e32 v146, 48, v160
	v_lshl_add_u64 v[170:171], v[152:153], 2, s[12:13]
	v_ashrrev_i32_e32 v149, 31, v148
	v_ashrrev_i32_e32 v147, 31, v146
	v_lshl_add_u64 v[172:173], v[148:149], 2, s[12:13]
	v_lshl_add_u64 v[174:175], v[146:147], 2, s[12:13]
	s_nop 0
	s_nop 0
	s_nop 0
	s_nop 0
	s_nop 0
	s_nop 0
	s_nop 0
	s_nop 0
	s_nop 0
	s_lshl_b32 s36, s3, 8
	v_readlane_b32 s60, v244, 0
	v_readlane_b32 s64, v244, 4
	v_readlane_b32 s65, v244, 5
	v_readlane_b32 s66, v244, 6
	v_readlane_b32 s67, v244, 7
	s_ashr_i32 s37, s36, 31
	v_readlane_b32 s61, v244, 1
	v_readlane_b32 s62, v244, 2
	v_readlane_b32 s63, v244, 3
	s_waitcnt vmcnt(0)
	v_mov_b32_e32 v150, v245
	v_mov_b32_e32 v154, v246
	v_mov_b32_e32 v156, v247
	v_mov_b32_e32 v158, v248
	v_mov_b32_e32 v162, v249
	v_mov_b32_e32 v170, v250
	v_mov_b32_e32 v171, v251
	v_mov_b32_e32 v169, v252
	v_fmamk_f32 v150, v150, 0x3a800000, v165
	v_mul_f32_e32 v164, 0x4f800000, v150
	v_cmp_gt_f32_e32 vcc, s54, v150
	v_fmamk_f32 v154, v154, 0x3a800000, v165
	s_nop 0
	v_cndmask_b32_e32 v150, v150, v164, vcc
	v_fmamk_f32 v156, v156, 0x3a800000, v165
	v_mul_f32_e32 v164, 0x4f800000, v154
	v_sqrt_f32_e32 v168, v150
	v_cmp_gt_f32_e64 s[2:3], s54, v154
	v_mul_f32_e32 v166, 0x4f800000, v156
	v_cmp_gt_f32_e64 s[4:5], s54, v156
	v_cndmask_b32_e64 v154, v154, v164, s[2:3]
	v_sqrt_f32_e32 v164, v154
	v_cndmask_b32_e64 v156, v156, v166, s[4:5]
	v_sqrt_f32_e32 v166, v156
	v_add_u32_e32 v173, -1, v168
	v_add_u32_e32 v174, 1, v168
	v_fma_f32 v175, -v173, v168, v150
	v_fma_f32 v176, -v174, v168, v150
	v_add_u32_e32 v177, -1, v164
	v_cmp_ge_f32_e64 s[6:7], 0, v175
	v_add_u32_e32 v179, -1, v166
	v_add_u32_e32 v178, 1, v164
	v_cndmask_b32_e64 v168, v168, v173, s[6:7]
	v_fma_f32 v173, -v177, v164, v154
	v_cmp_lt_f32_e64 s[6:7], 0, v176
	v_fma_f32 v181, -v179, v166, v156
	v_add_u32_e32 v180, 1, v166
	v_cndmask_b32_e64 v168, v168, v174, s[6:7]
	v_cmp_ge_f32_e64 s[6:7], 0, v173
	v_fma_f32 v175, -v178, v164, v154
	v_fma_f32 v183, -v180, v166, v156
	v_cndmask_b32_e64 v164, v164, v177, s[6:7]
	v_cmp_ge_f32_e64 s[6:7], 0, v181
	v_mul_f32_e32 v173, 0x37800000, v168
	v_cndmask_b32_e32 v168, v168, v173, vcc
	v_cndmask_b32_e64 v166, v166, v179, s[6:7]
	v_cmp_lt_f32_e64 s[6:7], 0, v175
	v_cmp_class_f32_e32 vcc, v150, v167
	v_fmamk_f32 v158, v158, 0x3a800000, v165
	v_cndmask_b32_e64 v164, v164, v178, s[6:7]
	v_cmp_lt_f32_e64 s[6:7], 0, v183
	v_mul_f32_e32 v173, 0x37800000, v164
	v_cndmask_b32_e32 v150, v168, v150, vcc
	v_cndmask_b32_e64 v166, v166, v180, s[6:7]
	v_cndmask_b32_e64 v164, v164, v173, s[2:3]
	v_div_scale_f32 v168, s[2:3], v150, v150, 1.0
	v_mul_f32_e32 v174, 0x37800000, v166
	v_cmp_class_f32_e64 s[2:3], v154, v167
	v_cndmask_b32_e64 v166, v166, v174, s[4:5]
	v_div_scale_f32 v173, vcc, 1.0, v150, 1.0
	v_cndmask_b32_e64 v154, v164, v154, s[2:3]
	v_cmp_class_f32_e64 s[2:3], v156, v167
	v_rcp_f32_e32 v164, v168
	v_mul_f32_e32 v172, 0x4f800000, v158
	v_cndmask_b32_e64 v156, v166, v156, s[2:3]
	v_div_scale_f32 v166, s[2:3], v154, v154, 1.0
	v_div_scale_f32 v175, s[4:5], v156, v156, 1.0
	v_rcp_f32_e32 v177, v166
	v_rcp_f32_e32 v178, v175
	v_fma_f32 v179, -v168, v164, 1.0
	v_fmac_f32_e32 v164, v179, v164
	v_fma_f32 v179, -v166, v177, 1.0
	v_div_scale_f32 v174, s[2:3], 1.0, v154, 1.0
	v_fma_f32 v180, -v175, v178, 1.0
	v_mul_f32_e32 v181, v173, v164
	v_fmac_f32_e32 v177, v179, v177
	v_fmac_f32_e32 v178, v180, v178
	v_fma_f32 v179, -v168, v181, v173
	v_mul_f32_e32 v180, v174, v177
	v_fmac_f32_e32 v181, v179, v164
	v_fma_f32 v179, -v166, v180, v174
	v_fma_f32 v168, -v168, v181, v173
	v_fmac_f32_e32 v180, v179, v177
	v_div_fmas_f32 v164, v168, v164, v181
	v_fma_f32 v166, -v166, v180, v174
	s_mov_b64 vcc, s[2:3]
	v_div_fixup_f32 v168, v164, v150, 1.0
	v_div_fmas_f32 v150, v166, v177, v180
	v_cmp_gt_f32_e32 vcc, s54, v158
	v_div_fixup_f32 v166, v150, v154, 1.0
	v_div_scale_f32 v176, s[4:5], 1.0, v156, 1.0
	v_cndmask_b32_e32 v150, v158, v172, vcc
	v_sqrt_f32_e32 v154, v150
	v_mul_f32_e32 v183, v176, v178
	v_fma_f32 v158, -v175, v183, v176
	v_fmac_f32_e32 v183, v158, v178
	v_add_u32_e32 v164, -1, v154
	v_fma_f32 v172, -v164, v154, v150
	v_cmp_ge_f32_e64 s[2:3], 0, v172
	v_add_u32_e32 v172, 1, v154
	v_fma_f32 v158, -v175, v183, v176
	v_cndmask_b32_e64 v164, v154, v164, s[2:3]
	v_fma_f32 v154, -v172, v154, v150
	v_cmp_lt_f32_e64 s[2:3], 0, v154
	v_fmamk_f32 v162, v162, 0x3a800000, v165
	v_mul_f32_e32 v173, 0x4f800000, v162
	v_cndmask_b32_e64 v154, v164, v172, s[2:3]
	v_mul_f32_e32 v164, 0x37800000, v154
	v_cndmask_b32_e32 v154, v154, v164, vcc
	v_cmp_class_f32_e32 vcc, v150, v167
	v_fmamk_f32 v169, v169, 0x3a800000, v165
	v_pk_mul_f32 v[106:107], v[106:107], v[166:167] op_sel_hi:[1,0]
	v_cndmask_b32_e32 v150, v154, v150, vcc
	v_div_scale_f32 v154, s[2:3], v150, v150, 1.0
	v_rcp_f32_e32 v172, v154
	s_mov_b64 vcc, s[4:5]
	v_div_fmas_f32 v158, v158, v178, v183
	v_cmp_gt_f32_e64 s[2:3], s54, v162
	v_div_fixup_f32 v164, v158, v156, 1.0
	v_fma_f32 v156, -v154, v172, 1.0
	v_cndmask_b32_e64 v162, v162, v173, s[2:3]
	v_fmac_f32_e32 v172, v156, v172
	v_div_scale_f32 v156, vcc, 1.0, v150, 1.0
	v_sqrt_f32_e32 v173, v162
	v_mul_f32_e32 v158, v156, v172
	v_fma_f32 v174, -v154, v158, v156
	v_fmac_f32_e32 v158, v174, v172
	v_fma_f32 v154, -v154, v158, v156
	v_add_u32_e32 v156, -1, v173
	v_fma_f32 v174, -v156, v173, v162
	v_cmp_ge_f32_e64 s[4:5], 0, v174
	v_add_u32_e32 v174, 1, v173
	v_div_fmas_f32 v154, v154, v172, v158
	v_cndmask_b32_e64 v156, v173, v156, s[4:5]
	v_fma_f32 v173, -v174, v173, v162
	v_cmp_lt_f32_e64 s[4:5], 0, v173
	v_fmamk_f32 v158, v170, 0x3a800000, v165
	v_mul_f32_e32 v170, 0x4f800000, v158
	v_cndmask_b32_e64 v156, v156, v174, s[4:5]
	v_mul_f32_e32 v173, 0x37800000, v156
	v_cndmask_b32_e64 v156, v156, v173, s[2:3]
	v_cmp_class_f32_e64 s[2:3], v162, v167
	v_pk_mul_f32 v[104:105], v[104:105], v[166:167] op_sel_hi:[1,0]
	v_pk_mul_f32 v[110:111], v[110:111], v[166:167] op_sel_hi:[1,0]
	v_cndmask_b32_e64 v156, v156, v162, s[2:3]
	v_div_scale_f32 v173, s[2:3], v156, v156, 1.0
	v_rcp_f32_e32 v174, v173
	v_cmp_gt_f32_e64 s[2:3], s54, v158
	v_div_fixup_f32 v162, v154, v150, 1.0
	v_pk_mul_f32 v[108:109], v[108:109], v[166:167] op_sel_hi:[1,0]
	v_cndmask_b32_e64 v158, v158, v170, s[2:3]
	v_fma_f32 v150, -v173, v174, 1.0
	v_sqrt_f32_e32 v170, v158
	v_fmac_f32_e32 v174, v150, v174
	v_div_scale_f32 v150, vcc, 1.0, v156, 1.0
	v_mul_f32_e32 v154, v150, v174
	v_fma_f32 v172, -v173, v154, v150
	v_fmac_f32_e32 v154, v172, v174
	v_add_u32_e32 v172, -1, v170
	v_fma_f32 v150, -v173, v154, v150
	v_fma_f32 v173, -v172, v170, v158
	v_cmp_ge_f32_e64 s[4:5], 0, v173
	v_add_u32_e32 v173, 1, v170
	v_div_fmas_f32 v150, v150, v174, v154
	v_cndmask_b32_e64 v172, v170, v172, s[4:5]
	v_fma_f32 v170, -v173, v170, v158
	v_cmp_lt_f32_e64 s[4:5], 0, v170
	v_max_f32_e32 v104, 0, v104
	v_max_f32_e32 v105, 0, v105
	v_cndmask_b32_e64 v170, v172, v173, s[4:5]
	v_mul_f32_e32 v172, 0x37800000, v170
	v_cndmask_b32_e64 v170, v170, v172, s[2:3]
	v_cmp_class_f32_e64 s[2:3], v158, v167
	v_max_f32_e32 v106, 0, v106
	v_max_f32_e32 v108, 0, v108
	v_cndmask_b32_e64 v170, v170, v158, s[2:3]
	v_div_scale_f32 v172, s[2:3], v170, v170, 1.0
	v_rcp_f32_e32 v173, v172
	v_div_fixup_f32 v158, v150, v156, 1.0
	v_fmamk_f32 v156, v171, 0x3a800000, v165
	v_mul_f32_e32 v171, 0x4f800000, v156
	v_cmp_gt_f32_e64 s[2:3], s54, v156
	v_fma_f32 v150, -v172, v173, 1.0
	v_fmac_f32_e32 v173, v150, v173
	v_cndmask_b32_e64 v156, v156, v171, s[2:3]
	v_div_scale_f32 v150, vcc, 1.0, v170, 1.0
	v_sqrt_f32_e32 v171, v156
	v_mul_f32_e32 v154, v150, v173
	v_fma_f32 v174, -v172, v154, v150
	v_fmac_f32_e32 v154, v174, v173
	v_fma_f32 v150, -v172, v154, v150
	v_add_u32_e32 v172, -1, v171
	v_fma_f32 v174, -v172, v171, v156
	v_cmp_ge_f32_e64 s[4:5], 0, v174
	v_add_u32_e32 v174, 1, v171
	v_div_fmas_f32 v150, v150, v173, v154
	v_cndmask_b32_e64 v172, v171, v172, s[4:5]
	v_fma_f32 v171, -v174, v171, v156
	v_cmp_lt_f32_e64 s[4:5], 0, v171
	v_mul_f32_e32 v108, v108, v108
	v_max_f32_e32 v107, 0, v107
	v_cndmask_b32_e64 v171, v172, v174, s[4:5]
	v_mul_f32_e32 v172, 0x37800000, v171
	v_cndmask_b32_e64 v171, v171, v172, s[2:3]
	v_cmp_class_f32_e64 s[2:3], v156, v167
	v_pk_mul_f32 v[96:97], v[96:97], v[166:167] op_sel_hi:[1,0]
	v_mul_f32_e32 v107, v107, v107
	v_cndmask_b32_e64 v171, v171, v156, s[2:3]
	v_div_scale_f32 v172, s[2:3], v171, v171, 1.0
	v_rcp_f32_e32 v174, v172
	v_div_fixup_f32 v156, v150, v170, 1.0
	v_mul_f32_e32 v170, 0x4f800000, v169
	v_cmp_gt_f32_e64 s[2:3], s54, v169
	v_fma_f32 v150, -v172, v174, 1.0
	v_fmac_f32_e32 v174, v150, v174
	v_cndmask_b32_e64 v169, v169, v170, s[2:3]
	v_div_scale_f32 v150, vcc, 1.0, v171, 1.0
	v_sqrt_f32_e32 v170, v169
	v_mul_f32_e32 v154, v150, v174
	v_fma_f32 v173, -v172, v154, v150
	v_fmac_f32_e32 v154, v173, v174
	v_fma_f32 v150, -v172, v154, v150
	v_add_u32_e32 v172, -1, v170
	v_fma_f32 v173, -v172, v170, v169
	v_cmp_ge_f32_e64 s[4:5], 0, v173
	v_add_u32_e32 v173, 1, v170
	v_div_fmas_f32 v150, v150, v174, v154
	v_cndmask_b32_e64 v172, v170, v172, s[4:5]
	v_fma_f32 v170, -v173, v170, v169
	v_cmp_lt_f32_e64 s[4:5], 0, v170
	v_div_fixup_f32 v154, v150, v171, 1.0
	v_pk_mul_f32 v[100:101], v[100:101], v[166:167] op_sel_hi:[1,0]
	v_cndmask_b32_e64 v170, v172, v173, s[4:5]
	v_mul_f32_e32 v172, 0x37800000, v170
	v_cndmask_b32_e64 v170, v170, v172, s[2:3]
	v_cmp_class_f32_e64 s[2:3], v169, v167
	s_mov_b64 s[4:5], s[64:65]
	s_mov_b64 s[6:7], s[66:67]
	v_cndmask_b32_e64 v169, v170, v169, s[2:3]
	v_div_scale_f32 v170, s[2:3], v169, v169, 1.0
	v_rcp_f32_e32 v172, v170
	v_pk_mul_f32 v[124:125], v[124:125], v[168:169] op_sel_hi:[1,0]
	v_pk_mul_f32 v[122:123], v[122:123], v[168:169] op_sel_hi:[1,0]
	v_pk_mul_f32 v[120:121], v[120:121], v[168:169] op_sel_hi:[1,0]
	v_fma_f32 v150, -v170, v172, 1.0
	v_fmac_f32_e32 v172, v150, v172
	v_div_scale_f32 v150, vcc, 1.0, v169, 1.0
	v_mul_f32_e32 v171, v150, v172
	v_fma_f32 v173, -v170, v171, v150
	v_fmac_f32_e32 v171, v173, v172
	v_fma_f32 v150, -v170, v171, v150
	v_div_fmas_f32 v150, v150, v172, v171
	v_pk_mul_f32 v[126:127], v[126:127], v[168:169] op_sel_hi:[1,0]
	v_max_f32_e32 v124, 0, v124
	v_max_f32_e32 v120, 0, v120
	v_max_f32_e32 v121, 0, v121
	v_max_f32_e32 v122, 0, v122
	v_div_fixup_f32 v150, v150, v169, 1.0
	v_mul_f32_e32 v124, v124, v124
	v_mul_f32_e32 v120, v120, v120
	v_max_f32_e32 v125, 0, v125
	v_mul_f32_e32 v121, v121, v121
	v_max_f32_e32 v126, 0, v126
	v_mul_f32_e32 v169, v122, v122
	v_max_f32_e32 v122, 0, v127
	v_max_f32_e32 v123, 0, v123
	v_mul_f32_e32 v125, v125, v125
	v_mul_f32_e32 v126, v126, v126
	v_mul_f32_e32 v127, v122, v122
	v_mul_f32_e32 v170, v123, v123
	v_cvt_pk_bf16_f32 v122, v124, v125
	v_cvt_pk_bf16_f32 v123, v126, v127
	v_cvt_pk_bf16_f32 v124, v120, v121
	v_lshlrev_b64 v[120:121], 13, v[160:161]
	v_lshl_add_u64 v[120:121], s[6:7], 0, v[120:121]
	s_lshl_b64 s[2:3], s[36:37], 1
	v_lshl_add_u64 v[120:121], v[120:121], 0, s[2:3]
	v_pk_mul_f32 v[112:113], v[112:113], v[168:169] op_sel_hi:[1,0]
	v_lshl_add_u64 v[120:121], v[120:121], 0, v[136:137]
	v_pk_mul_f32 v[116:117], v[116:117], v[168:169] op_sel_hi:[1,0]
	v_pk_mul_f32 v[114:115], v[114:115], v[168:169] op_sel_hi:[1,0]
	v_max_f32_e32 v112, 0, v112
	v_cvt_pk_bf16_f32 v125, v169, v170
	global_store_dwordx4 v[120:121], v[122:125], off
	v_pk_mul_f32 v[118:119], v[118:119], v[168:169] op_sel_hi:[1,0]
	v_max_f32_e32 v113, 0, v113
	v_mul_f32_e32 v122, v112, v112
	v_max_f32_e32 v112, 0, v117
	v_max_f32_e32 v114, 0, v114
	v_max_f32_e32 v116, 0, v116
	v_mul_f32_e32 v112, v112, v112
	v_mul_f32_e32 v117, v113, v113
	v_max_f32_e32 v113, 0, v118
	v_mul_f32_e32 v118, v114, v114
	v_max_f32_e32 v114, 0, v119
	v_max_f32_e32 v115, 0, v115
	v_mul_f32_e32 v116, v116, v116
	v_mul_f32_e32 v113, v113, v113
	v_mul_f32_e32 v114, v114, v114
	v_mul_f32_e32 v115, v115, v115
	v_cvt_pk_bf16_f32 v112, v116, v112
	v_cvt_pk_bf16_f32 v113, v113, v114
	v_cvt_pk_bf16_f32 v114, v122, v117
	v_cvt_pk_bf16_f32 v115, v118, v115
	global_store_dwordx4 v[120:121], v[112:115], off offset:256
	v_pk_mul_f32 v[98:99], v[98:99], v[166:167] op_sel_hi:[1,0]
	v_max_f32_e32 v96, 0, v96
	v_mul_f32_e32 v112, v104, v104
	v_max_f32_e32 v104, 0, v109
	v_mul_f32_e32 v109, v105, v105
	v_max_f32_e32 v105, 0, v110
	v_mul_f32_e32 v110, v106, v106
	v_max_f32_e32 v106, 0, v111
	v_mul_f32_e32 v104, v104, v104
	v_mul_f32_e32 v105, v105, v105
	v_mul_f32_e32 v106, v106, v106
	v_cvt_pk_bf16_f32 v104, v108, v104
	v_cvt_pk_bf16_f32 v105, v105, v106
	v_cvt_pk_bf16_f32 v106, v112, v109
	v_lshlrev_b64 v[108:109], 13, v[152:153]
	v_lshl_add_u64 v[108:109], s[6:7], 0, v[108:109]
	v_lshl_add_u64 v[108:109], v[108:109], 0, s[2:3]
	v_lshl_add_u64 v[108:109], v[108:109], 0, v[136:137]
	v_cvt_pk_bf16_f32 v107, v110, v107
	global_store_dwordx4 v[108:109], v[104:107], off
	v_pk_mul_f32 v[102:103], v[102:103], v[166:167] op_sel_hi:[1,0]
	v_max_f32_e32 v97, 0, v97
	v_mul_f32_e32 v104, v96, v96
	v_max_f32_e32 v96, 0, v101
	v_max_f32_e32 v98, 0, v98
	v_max_f32_e32 v100, 0, v100
	v_mul_f32_e32 v96, v96, v96
	v_mul_f32_e32 v101, v97, v97
	v_max_f32_e32 v97, 0, v102
	v_mul_f32_e32 v102, v98, v98
	v_max_f32_e32 v98, 0, v103
	v_max_f32_e32 v99, 0, v99
	v_pk_mul_f32 v[90:91], v[90:91], v[164:165] op_sel_hi:[1,0]
	v_pk_mul_f32 v[88:89], v[88:89], v[164:165] op_sel_hi:[1,0]
	v_mul_f32_e32 v100, v100, v100
	v_mul_f32_e32 v97, v97, v97
	v_mul_f32_e32 v98, v98, v98
	v_mul_f32_e32 v99, v99, v99
	v_cvt_pk_bf16_f32 v96, v100, v96
	v_pk_mul_f32 v[94:95], v[94:95], v[164:165] op_sel_hi:[1,0]
	v_pk_mul_f32 v[92:93], v[92:93], v[164:165] op_sel_hi:[1,0]
	v_max_f32_e32 v88, 0, v88
	v_max_f32_e32 v89, 0, v89
	v_max_f32_e32 v90, 0, v90
	v_cvt_pk_bf16_f32 v97, v97, v98
	v_cvt_pk_bf16_f32 v98, v104, v101
	v_cvt_pk_bf16_f32 v99, v102, v99
	global_store_dwordx4 v[108:109], v[96:99], off offset:256
	v_max_f32_e32 v92, 0, v92
	v_mul_f32_e32 v92, v92, v92
	v_mul_f32_e32 v96, v88, v88
	v_max_f32_e32 v88, 0, v93
	v_mul_f32_e32 v93, v89, v89
	v_max_f32_e32 v89, 0, v94
	v_mul_f32_e32 v94, v90, v90
	v_max_f32_e32 v90, 0, v95
	v_mul_f32_e32 v88, v88, v88
	v_mul_f32_e32 v89, v89, v89
	v_mul_f32_e32 v90, v90, v90
	v_cvt_pk_bf16_f32 v88, v92, v88
	v_cvt_pk_bf16_f32 v89, v89, v90
	v_cvt_pk_bf16_f32 v90, v96, v93
	v_lshlrev_b64 v[92:93], 13, v[148:149]
	v_lshl_add_u64 v[92:93], s[6:7], 0, v[92:93]
	v_max_f32_e32 v91, 0, v91
	v_lshl_add_u64 v[92:93], v[92:93], 0, s[2:3]
	v_pk_mul_f32 v[80:81], v[80:81], v[164:165] op_sel_hi:[1,0]
	v_mul_f32_e32 v91, v91, v91
	v_lshl_add_u64 v[92:93], v[92:93], 0, v[136:137]
	v_pk_mul_f32 v[84:85], v[84:85], v[164:165] op_sel_hi:[1,0]
	v_pk_mul_f32 v[82:83], v[82:83], v[164:165] op_sel_hi:[1,0]
	v_max_f32_e32 v80, 0, v80
	v_cvt_pk_bf16_f32 v91, v94, v91
	global_store_dwordx4 v[92:93], v[88:91], off
	v_pk_mul_f32 v[86:87], v[86:87], v[164:165] op_sel_hi:[1,0]
	v_max_f32_e32 v81, 0, v81
	v_mul_f32_e32 v88, v80, v80
	v_max_f32_e32 v80, 0, v85
	v_max_f32_e32 v82, 0, v82
	v_max_f32_e32 v84, 0, v84
	v_mul_f32_e32 v80, v80, v80
	v_mul_f32_e32 v85, v81, v81
	v_max_f32_e32 v81, 0, v86
	v_mul_f32_e32 v86, v82, v82
	v_max_f32_e32 v82, 0, v87
	v_max_f32_e32 v83, 0, v83
	v_pk_mul_f32 v[74:75], v[74:75], v[162:163] op_sel_hi:[1,0]
	v_pk_mul_f32 v[72:73], v[72:73], v[162:163] op_sel_hi:[1,0]
	v_mul_f32_e32 v84, v84, v84
	v_mul_f32_e32 v81, v81, v81
	v_mul_f32_e32 v82, v82, v82
	v_mul_f32_e32 v83, v83, v83
	v_cvt_pk_bf16_f32 v80, v84, v80
	v_pk_mul_f32 v[78:79], v[78:79], v[162:163] op_sel_hi:[1,0]
	v_pk_mul_f32 v[76:77], v[76:77], v[162:163] op_sel_hi:[1,0]
	v_max_f32_e32 v72, 0, v72
	v_max_f32_e32 v73, 0, v73
	v_max_f32_e32 v74, 0, v74
	v_cvt_pk_bf16_f32 v81, v81, v82
	v_cvt_pk_bf16_f32 v82, v88, v85
	v_cvt_pk_bf16_f32 v83, v86, v83
	global_store_dwordx4 v[92:93], v[80:83], off offset:256
	v_max_f32_e32 v76, 0, v76
	v_mul_f32_e32 v76, v76, v76
	v_mul_f32_e32 v80, v72, v72
	v_max_f32_e32 v72, 0, v77
	v_mul_f32_e32 v77, v73, v73
	v_max_f32_e32 v73, 0, v78
	v_mul_f32_e32 v78, v74, v74
	v_max_f32_e32 v74, 0, v79
	v_mul_f32_e32 v72, v72, v72
	v_mul_f32_e32 v73, v73, v73
	v_mul_f32_e32 v74, v74, v74
	v_cvt_pk_bf16_f32 v72, v76, v72
	v_cvt_pk_bf16_f32 v73, v73, v74
	v_cvt_pk_bf16_f32 v74, v80, v77
	v_lshlrev_b64 v[76:77], 13, v[146:147]
	v_lshl_add_u64 v[76:77], s[6:7], 0, v[76:77]
	v_max_f32_e32 v75, 0, v75
	v_lshl_add_u64 v[76:77], v[76:77], 0, s[2:3]
	v_pk_mul_f32 v[64:65], v[64:65], v[162:163] op_sel_hi:[1,0]
	v_mul_f32_e32 v75, v75, v75
	v_lshl_add_u64 v[76:77], v[76:77], 0, v[136:137]
	v_pk_mul_f32 v[68:69], v[68:69], v[162:163] op_sel_hi:[1,0]
	v_pk_mul_f32 v[66:67], v[66:67], v[162:163] op_sel_hi:[1,0]
	v_max_f32_e32 v64, 0, v64
	v_cvt_pk_bf16_f32 v75, v78, v75
	global_store_dwordx4 v[76:77], v[72:75], off
	v_pk_mul_f32 v[70:71], v[70:71], v[162:163] op_sel_hi:[1,0]
	v_max_f32_e32 v65, 0, v65
	v_mul_f32_e32 v72, v64, v64
	v_max_f32_e32 v64, 0, v69
	v_max_f32_e32 v66, 0, v66
	v_max_f32_e32 v68, 0, v68
	v_mul_f32_e32 v64, v64, v64
	v_mul_f32_e32 v69, v65, v65
	v_max_f32_e32 v65, 0, v70
	v_mul_f32_e32 v70, v66, v66
	v_max_f32_e32 v66, 0, v71
	v_max_f32_e32 v67, 0, v67
	v_pk_mul_f32 v[58:59], v[58:59], v[158:159] op_sel_hi:[1,0]
	v_pk_mul_f32 v[56:57], v[56:57], v[158:159] op_sel_hi:[1,0]
	v_mul_f32_e32 v68, v68, v68
	v_mul_f32_e32 v65, v65, v65
	v_mul_f32_e32 v66, v66, v66
	v_mul_f32_e32 v67, v67, v67
	v_cvt_pk_bf16_f32 v64, v68, v64
	v_pk_mul_f32 v[62:63], v[62:63], v[158:159] op_sel_hi:[1,0]
	v_pk_mul_f32 v[60:61], v[60:61], v[158:159] op_sel_hi:[1,0]
	v_max_f32_e32 v56, 0, v56
	v_max_f32_e32 v57, 0, v57
	v_max_f32_e32 v58, 0, v58
	v_cvt_pk_bf16_f32 v65, v65, v66
	v_cvt_pk_bf16_f32 v66, v72, v69
	v_cvt_pk_bf16_f32 v67, v70, v67
	global_store_dwordx4 v[76:77], v[64:67], off offset:256
	v_max_f32_e32 v59, 0, v59
	v_max_f32_e32 v60, 0, v60
	v_mul_f32_e32 v64, v56, v56
	v_max_f32_e32 v56, 0, v61
	v_mul_f32_e32 v61, v57, v57
	v_max_f32_e32 v57, 0, v62
	v_mul_f32_e32 v62, v58, v58
	v_max_f32_e32 v58, 0, v63
	v_mul_f32_e32 v56, v56, v56
	v_mul_f32_e32 v57, v57, v57
	v_mul_f32_e32 v58, v58, v58
	v_mul_f32_e32 v59, v59, v59
	v_mul_f32_e32 v60, v60, v60
	v_cvt_pk_bf16_f32 v56, v60, v56
	v_cvt_pk_bf16_f32 v57, v57, v58
	v_cvt_pk_bf16_f32 v58, v64, v61
	v_cvt_pk_bf16_f32 v59, v62, v59
	v_add_co_u32_e32 v62, vcc, s55, v120
	v_pk_mul_f32 v[48:49], v[48:49], v[158:159] op_sel_hi:[1,0]
	s_nop 0
	v_addc_co_u32_e32 v63, vcc, 0, v121, vcc
	v_pk_mul_f32 v[52:53], v[52:53], v[158:159] op_sel_hi:[1,0]
	v_pk_mul_f32 v[50:51], v[50:51], v[158:159] op_sel_hi:[1,0]
	v_max_f32_e32 v48, 0, v48
	global_store_dwordx4 v[62:63], v[56:59], off
	v_pk_mul_f32 v[54:55], v[54:55], v[158:159] op_sel_hi:[1,0]
	v_max_f32_e32 v49, 0, v49
	v_mul_f32_e32 v56, v48, v48
	v_max_f32_e32 v48, 0, v53
	v_max_f32_e32 v50, 0, v50
	v_max_f32_e32 v52, 0, v52
	v_mul_f32_e32 v48, v48, v48
	v_mul_f32_e32 v53, v49, v49
	v_max_f32_e32 v49, 0, v54
	v_mul_f32_e32 v54, v50, v50
	v_max_f32_e32 v50, 0, v55
	v_max_f32_e32 v51, 0, v51
	v_pk_mul_f32 v[42:43], v[42:43], v[156:157] op_sel_hi:[1,0]
	v_pk_mul_f32 v[40:41], v[40:41], v[156:157] op_sel_hi:[1,0]
	v_lshl_add_u64 v[60:61], v[120:121], 0, s[18:19]
	v_mul_f32_e32 v52, v52, v52
	v_mul_f32_e32 v49, v49, v49
	v_mul_f32_e32 v50, v50, v50
	v_mul_f32_e32 v51, v51, v51
	v_cvt_pk_bf16_f32 v48, v52, v48
	v_pk_mul_f32 v[46:47], v[46:47], v[156:157] op_sel_hi:[1,0]
	v_pk_mul_f32 v[44:45], v[44:45], v[156:157] op_sel_hi:[1,0]
	v_max_f32_e32 v40, 0, v40
	v_max_f32_e32 v41, 0, v41
	v_max_f32_e32 v42, 0, v42
	v_cvt_pk_bf16_f32 v49, v49, v50
	v_cvt_pk_bf16_f32 v50, v56, v53
	v_cvt_pk_bf16_f32 v51, v54, v51
	global_store_dwordx4 v[60:61], v[48:51], off offset:256
	v_max_f32_e32 v43, 0, v43
	v_max_f32_e32 v44, 0, v44
	v_mul_f32_e32 v48, v40, v40
	v_max_f32_e32 v40, 0, v45
	v_mul_f32_e32 v45, v41, v41
	v_max_f32_e32 v41, 0, v46
	v_mul_f32_e32 v46, v42, v42
	v_max_f32_e32 v42, 0, v47
	v_mul_f32_e32 v40, v40, v40
	v_mul_f32_e32 v41, v41, v41
	v_mul_f32_e32 v42, v42, v42
	v_mul_f32_e32 v43, v43, v43
	v_mul_f32_e32 v44, v44, v44
	v_cvt_pk_bf16_f32 v40, v44, v40
	v_cvt_pk_bf16_f32 v41, v41, v42
	v_cvt_pk_bf16_f32 v42, v48, v45
	v_cvt_pk_bf16_f32 v43, v46, v43
	v_add_co_u32_e32 v46, vcc, s56, v120
	v_pk_mul_f32 v[32:33], v[32:33], v[156:157] op_sel_hi:[1,0]
	s_nop 0
	v_addc_co_u32_e32 v47, vcc, 0, v121, vcc
	v_pk_mul_f32 v[36:37], v[36:37], v[156:157] op_sel_hi:[1,0]
	v_pk_mul_f32 v[34:35], v[34:35], v[156:157] op_sel_hi:[1,0]
	v_max_f32_e32 v32, 0, v32
	global_store_dwordx4 v[46:47], v[40:43], off
	v_pk_mul_f32 v[38:39], v[38:39], v[156:157] op_sel_hi:[1,0]
	v_max_f32_e32 v33, 0, v33
	v_mul_f32_e32 v40, v32, v32
	v_max_f32_e32 v32, 0, v37
	v_max_f32_e32 v34, 0, v34
	v_max_f32_e32 v36, 0, v36
	v_mul_f32_e32 v32, v32, v32
	v_mul_f32_e32 v37, v33, v33
	v_max_f32_e32 v33, 0, v38
	v_mul_f32_e32 v38, v34, v34
	v_max_f32_e32 v34, 0, v39
	v_max_f32_e32 v35, 0, v35
	v_pk_mul_f32 v[26:27], v[26:27], v[154:155] op_sel_hi:[1,0]
	v_pk_mul_f32 v[24:25], v[24:25], v[154:155] op_sel_hi:[1,0]
	v_lshl_add_u64 v[44:45], v[120:121], 0, s[20:21]
	v_mul_f32_e32 v36, v36, v36
	v_mul_f32_e32 v33, v33, v33
	v_mul_f32_e32 v34, v34, v34
	v_mul_f32_e32 v35, v35, v35
	v_cvt_pk_bf16_f32 v32, v36, v32
	v_pk_mul_f32 v[30:31], v[30:31], v[154:155] op_sel_hi:[1,0]
	v_pk_mul_f32 v[28:29], v[28:29], v[154:155] op_sel_hi:[1,0]
	v_max_f32_e32 v24, 0, v24
	v_max_f32_e32 v25, 0, v25
	v_max_f32_e32 v26, 0, v26
	v_cvt_pk_bf16_f32 v33, v33, v34
	v_cvt_pk_bf16_f32 v34, v40, v37
	v_cvt_pk_bf16_f32 v35, v38, v35
	global_store_dwordx4 v[44:45], v[32:35], off offset:256
	v_max_f32_e32 v27, 0, v27
	v_max_f32_e32 v28, 0, v28
	v_mul_f32_e32 v32, v24, v24
	v_max_f32_e32 v24, 0, v29
	v_mul_f32_e32 v29, v25, v25
	v_max_f32_e32 v25, 0, v30
	v_mul_f32_e32 v30, v26, v26
	v_max_f32_e32 v26, 0, v31
	v_mul_f32_e32 v24, v24, v24
	v_mul_f32_e32 v25, v25, v25
	v_mul_f32_e32 v26, v26, v26
	v_mul_f32_e32 v27, v27, v27
	v_mul_f32_e32 v28, v28, v28
	v_cvt_pk_bf16_f32 v24, v28, v24
	v_cvt_pk_bf16_f32 v25, v25, v26
	v_cvt_pk_bf16_f32 v26, v32, v29
	v_cvt_pk_bf16_f32 v27, v30, v27
	v_add_co_u32_e32 v30, vcc, s57, v120
	v_pk_mul_f32 v[16:17], v[16:17], v[154:155] op_sel_hi:[1,0]
	s_nop 0
	v_addc_co_u32_e32 v31, vcc, 0, v121, vcc
	v_pk_mul_f32 v[20:21], v[20:21], v[154:155] op_sel_hi:[1,0]
	v_pk_mul_f32 v[18:19], v[18:19], v[154:155] op_sel_hi:[1,0]
	v_max_f32_e32 v16, 0, v16
	global_store_dwordx4 v[30:31], v[24:27], off
	v_pk_mul_f32 v[22:23], v[22:23], v[154:155] op_sel_hi:[1,0]
	v_max_f32_e32 v17, 0, v17
	v_mul_f32_e32 v24, v16, v16
	v_max_f32_e32 v16, 0, v21
	v_max_f32_e32 v18, 0, v18
	v_max_f32_e32 v20, 0, v20
	v_mul_f32_e32 v16, v16, v16
	v_mul_f32_e32 v21, v17, v17
	v_max_f32_e32 v17, 0, v22
	v_mul_f32_e32 v22, v18, v18
	v_max_f32_e32 v18, 0, v23
	v_max_f32_e32 v19, 0, v19
	v_pk_mul_f32 v[10:11], v[10:11], v[150:151] op_sel_hi:[1,0]
	v_pk_mul_f32 v[8:9], v[8:9], v[150:151] op_sel_hi:[1,0]
	v_lshl_add_u64 v[28:29], v[120:121], 0, s[22:23]
	v_mul_f32_e32 v20, v20, v20
	v_mul_f32_e32 v17, v17, v17
	v_mul_f32_e32 v18, v18, v18
	v_mul_f32_e32 v19, v19, v19
	v_cvt_pk_bf16_f32 v16, v20, v16
	v_pk_mul_f32 v[14:15], v[14:15], v[150:151] op_sel_hi:[1,0]
	v_pk_mul_f32 v[12:13], v[12:13], v[150:151] op_sel_hi:[1,0]
	v_max_f32_e32 v8, 0, v8
	v_max_f32_e32 v9, 0, v9
	v_max_f32_e32 v10, 0, v10
	v_cvt_pk_bf16_f32 v17, v17, v18
	v_cvt_pk_bf16_f32 v18, v24, v21
	v_cvt_pk_bf16_f32 v19, v22, v19
	global_store_dwordx4 v[28:29], v[16:19], off offset:256
	v_max_f32_e32 v11, 0, v11
	v_max_f32_e32 v12, 0, v12
	v_mul_f32_e32 v16, v8, v8
	v_max_f32_e32 v8, 0, v13
	v_mul_f32_e32 v13, v9, v9
	v_max_f32_e32 v9, 0, v14
	v_mul_f32_e32 v14, v10, v10
	v_max_f32_e32 v10, 0, v15
	v_mul_f32_e32 v8, v8, v8
	v_mul_f32_e32 v9, v9, v9
	v_mul_f32_e32 v10, v10, v10
	v_mul_f32_e32 v11, v11, v11
	v_mul_f32_e32 v12, v12, v12
	v_cvt_pk_bf16_f32 v8, v12, v8
	v_cvt_pk_bf16_f32 v9, v9, v10
	v_cvt_pk_bf16_f32 v10, v16, v13
	v_cvt_pk_bf16_f32 v11, v14, v11
	v_add_co_u32_e32 v14, vcc, s58, v120
	v_pk_mul_f32 v[2:3], v[2:3], v[150:151] op_sel_hi:[1,0]
	v_pk_mul_f32 v[0:1], v[0:1], v[150:151] op_sel_hi:[1,0]
	v_addc_co_u32_e32 v15, vcc, 0, v121, vcc
	v_pk_mul_f32 v[6:7], v[6:7], v[150:151] op_sel_hi:[1,0]
	v_pk_mul_f32 v[4:5], v[4:5], v[150:151] op_sel_hi:[1,0]
	v_max_f32_e32 v0, 0, v0
	v_max_f32_e32 v1, 0, v1
	v_max_f32_e32 v2, 0, v2
	global_store_dwordx4 v[14:15], v[8:11], off
	v_max_f32_e32 v3, 0, v3
	v_lshl_add_u64 v[12:13], v[120:121], 0, s[24:25]
	v_mul_f32_e32 v8, v0, v0
	v_max_f32_e32 v0, 0, v5
	v_mul_f32_e32 v5, v1, v1
	v_max_f32_e32 v1, 0, v6
	v_mul_f32_e32 v6, v2, v2
	v_max_f32_e32 v2, 0, v7
	v_max_f32_e32 v4, 0, v4
	v_mul_f32_e32 v0, v0, v0
	v_mul_f32_e32 v1, v1, v1
	v_mul_f32_e32 v2, v2, v2
	v_mul_f32_e32 v3, v3, v3
	s_andn2_b64 vcc, exec, s[0:1]
	s_mov_b64 s[0:1], -1
	v_mul_f32_e32 v4, v4, v4
	v_cvt_pk_bf16_f32 v0, v4, v0
	v_cvt_pk_bf16_f32 v1, v1, v2
	v_cvt_pk_bf16_f32 v2, v8, v5
	v_cvt_pk_bf16_f32 v3, v6, v3
	global_store_dwordx4 v[12:13], v[0:3], off offset:256
	s_cbranch_vccnz .LBB0_2105
	s_andn2_b64 vcc, exec, s[10:11]
	s_cbranch_vccnz .LBB0_2104
	s_barrier
	s_branch .LBB0_2104
